# baseline (speedup 1.0000x reference)
; template <bool OUTF>
; DEV void rmsnorm_rows(const float* __restrict__ x, const float* __restrict__ g, void* outp, int rows, int gwave, int nwaves, int lane) {
;     for (int r = gwave; r < rows; r += nwaves) {
;         const f32x4* xr = (const f32x4*)(x + (size_t)r * 2048); f32x4 v[8]; float ss = 0.f;
; #pragma unroll
;         for (int i = 0; i < 8; ++i) { v[i] = xr[lane + 64 * i]; ss += v[i][0] * v[i][0] + v[i][1] * v[i][1] + v[i][2] * v[i][2] + v[i][3] * v[i][3]; }
; DEV void run_phase(const P& p, int ph, LAS unsigned char* lds) {
;     ...
;     switch (ph) {
;     case PH_PREP: {
;         conv_job(p, 0, gtid, gthreads);
;         u16* TRIL = (u16*)(ws + O_TRIL);
;         for (int i = gtid; i < 4 * 128 * 128; i += gthreads) { const int ii = (i >> 7) & 127, jj = i & 127; TRIL[i] = f2bf(jj <= ii ? p.gm_ws[i] : 0.f); }
;         float* cosT = (float*)(ws + O_ROPE); float* sinT = cosT + 8192 * 8;
;         for (int i = gtid; i < 8192 * 8; i += gthreads) { const float ang = (float)p.pos[i >> 3] * p.invf[i & 7]; cosT[i] = cosf(ang); sinT[i] = sinf(ang); }
;         if (G != 256) for (int i = gtid; i < 8 * 8192 * 8; i += gthreads) SS[8192 * 8 + i] = 0.f;
;         prep_rows(p.x, XB, SS, 8192, gwave, nwaves, lane);
;         for (int l = 0; l < 2; ++l) rmsnorm_rows<false>(p.mem, p.norm_mem + l * 2048, (u16*)(ws + O_MEMN) + (size_t)l * 256 * 2048, 256, gwave, nwaves, lane);
;     } break;
;     case L0_GU1: case L1_GU1: case L0_GU2: case L1_GU2: {
;         const int second = (ph == L0_GU2 || ph == L1_GU2) ? 1 : 0; const int k = 2 * L + second; EpiSwiglu E{ACT, SS + (size_t)(4 * L + (second ? 3 : 0)) * 65536};
;         run_gemm(lds, XB, (const u16*)(ws + O_WGU + k * SZ_WGU), 8192, 11264, 2048, E, bx);
;         idle_conv(p, (ph == L0_GU1) ? 1 : (ph == L0_GU2) ? 4 : (ph == L1_GU1) ? 5 : 8, 32 * 44, bx, G);
;     } break;
;     case L0_DN1: case L1_DN1: case L0_DN2: case L1_DN2: {
;         const int second = (ph == L0_DN2 || ph == L1_DN2) ? 1 : 0; const int k = 2 * L + second; const bool lastp = (ph == L1_DN2);
;         run_resid_gemm(lds, ACT, (const u16*)(ws + O_WDN + k * SZ_WDN), 5632, (ph == L0_DN1) ? p.x : XW, XW, 0.5f, lastp ? nullptr : XB, lastp ? nullptr : SS + (size_t)(4 * L + (second ? 4 : 1)) * 65536, bx, G);
;     } break;
;     case PH_FINAL: rmsnorm_rows<true>(XW, p.final_norm, p.out, 8192, gwave, nwaves, lane); break;
.LBB0_22:
	v_mov_b32_e32 v173, v198
	v_readlane_b32 s1, v250, 0
	v_readlane_b32 s4, v250, 1
	v_readfirstlane_b32 s0, v173
	s_ashr_i32 s0, s0, 6
	v_writelane_b32 v254, s1, 20
	s_lshl_b32 s1, s1, 3
	s_add_i32 s0, s1, s0
	v_writelane_b32 v254, s0, 21
	v_readlane_b32 s5, v250, 2
	s_mov_b64 s[6:7], 0
	v_writelane_b32 v254, s1, 22
	v_writelane_b32 v254, s4, 23
	s_lshl_b32 s0, s4, 3
	v_readlane_b32 s4, v250, 7
	v_writelane_b32 v254, s0, 24
	s_cmp_gt_i32 s4, 13
	v_readlane_b32 s5, v250, 8
	v_writelane_b32 v254, s1, 25
	s_cselect_b64 s[0:1], -1, 0
	v_writelane_b32 v254, s0, 26
	s_cmp_lt_i32 s4, 12
	s_mov_b64 s[4:5], 0
	v_writelane_b32 v254, s1, 27
	v_writelane_b32 v254, s6, 28
	v_and_b32_e32 v172, 63, v173
	s_mov_b64 s[0:1], -1
	v_writelane_b32 v254, s7, 29
	v_writelane_b32 v254, s4, 30
	s_mov_b64 s[70:71], 0
	s_nop 0
	v_writelane_b32 v254, s5, 31
	s_mov_b64 s[4:5], 0
	v_writelane_b32 v254, s4, 32
	s_nop 1
	v_writelane_b32 v254, s5, 33
	s_mov_b64 s[4:5], 0
	v_writelane_b32 v254, s4, 34
	s_nop 1
	v_writelane_b32 v254, s5, 35
	s_mov_b64 s[4:5], 0
	v_writelane_b32 v254, s4, 36
	s_nop 1
	v_writelane_b32 v254, s5, 37
	s_cbranch_scc1 .LBB0_231
	v_readlane_b32 s4, v250, 7
	s_cmp_gt_i32 s4, 17
	v_readlane_b32 s5, v250, 8
	s_cbranch_scc0 .LBB0_40
	s_mov_b64 s[6:7], 0
	v_writelane_b32 v254, s6, 32
	s_cmp_gt_i32 s4, 20
	s_mov_b64 s[4:5], 0
	v_writelane_b32 v254, s7, 33
	v_writelane_b32 v254, s4, 30
	s_nop 1
	v_writelane_b32 v254, s5, 31
	s_mov_b64 s[4:5], 0
	v_writelane_b32 v254, s4, 36
	s_nop 1
	v_writelane_b32 v254, s5, 37
	s_cbranch_scc0 .LBB0_37
	s_mov_b64 s[4:5], 0
	v_writelane_b32 v254, s4, 30
	s_nop 1
	v_writelane_b32 v254, s5, 31
	v_readlane_b32 s4, v250, 7
	v_readlane_b32 s5, v250, 8
	s_cmp_gt_i32 s4, 22
	v_readlane_b32 s4, v252, 4
	v_readlane_b32 s18, v252, 18
	v_readlane_b32 s19, v252, 19
	v_readlane_b32 s5, v252, 5
	v_readlane_b32 s6, v252, 6
	v_readlane_b32 s7, v252, 7
	v_readlane_b32 s8, v252, 8
	v_readlane_b32 s9, v252, 9
	v_readlane_b32 s10, v252, 10
	v_readlane_b32 s11, v252, 11
	v_readlane_b32 s12, v252, 12
	v_readlane_b32 s13, v252, 13
	v_readlane_b32 s14, v252, 14
	v_readlane_b32 s15, v252, 15
	v_readlane_b32 s16, v252, 16
	v_readlane_b32 s17, v252, 17
	s_cbranch_scc0 .LBB0_34
	v_readlane_b32 s0, v250, 7
	s_cmp_gt_i32 s0, 23
	s_mov_b64 s[70:71], -1
	v_readlane_b32 s1, v250, 8
	s_cbranch_scc0 .LBB0_33
	v_readlane_b32 s0, v250, 7
	s_cmp_eq_u32 s0, 24
	v_readlane_b32 s1, v250, 8
	s_cbranch_scc0 .LBB0_32
	v_readlane_b32 s0, v254, 21
	s_cmpk_gt_i32 s0, 0x1fff
	v_readlane_b32 s1, v254, 22
	s_cbranch_scc1 .LBB0_32
	v_lshlrev_b32_e32 v160, 4, v172
	global_load_dwordx4 v[0:3], v160, s[18:19]
	global_load_dwordx4 v[4:7], v160, s[18:19] offset:1024
	global_load_dwordx4 v[8:11], v160, s[18:19] offset:2048
	global_load_dwordx4 v[12:15], v160, s[18:19] offset:3072
	v_or_b32_e32 v16, 0x1000, v160
	v_or_b32_e32 v20, 0x1400, v160
	v_or_b32_e32 v24, 0x1800, v160
	v_or_b32_e32 v28, 0x1c00, v160
	global_load_dwordx4 v[16:19], v16, s[18:19]
	s_nop 0
	global_load_dwordx4 v[20:23], v20, s[18:19]
	s_nop 0
	global_load_dwordx4 v[24:27], v24, s[18:19]
	s_nop 0
	global_load_dwordx4 v[28:31], v28, s[18:19]
	v_cmp_lt_i32_e32 vcc, v207, v206
	v_readlane_b32 s0, v254, 21
	s_mov_b32 s10, s0
	v_cndmask_b32_e32 v32, v204, v207, vcc
	v_cmp_lt_i32_e32 vcc, v208, v206
	s_ashr_i32 s11, s0, 31
	v_lshlrev_b32_e32 v65, 2, v32
	v_cndmask_b32_e32 v32, v204, v208, vcc
	v_cmp_lt_i32_e32 vcc, v209, v206
	s_lshl_b64 s[6:7], s[10:11], 13
	v_readlane_b32 s12, v254, 24
	v_lshlrev_b32_e32 v66, 2, v32
	v_cndmask_b32_e32 v32, v204, v209, vcc
	v_cmp_lt_i32_e32 vcc, v210, v206
	v_readlane_b32 s1, v254, 22
	s_add_u32 s0, s90, s6
	v_readlane_b32 s13, v254, 25
	v_lshlrev_b32_e32 v67, 2, v32
	v_cndmask_b32_e32 v32, v204, v210, vcc
	v_cmp_lt_i32_e32 vcc, v211, v206
	s_addc_u32 s1, s91, s7
	s_ashr_i32 s13, s12, 31
	v_lshlrev_b32_e32 v68, 2, v32
	v_cndmask_b32_e32 v32, v204, v211, vcc
	v_cmp_lt_i32_e32 vcc, v212, v206
	s_lshl_b64 s[4:5], s[12:13], 13
	s_mov_b32 s8, s10
	v_lshlrev_b32_e32 v69, 2, v32
	v_cndmask_b32_e32 v32, v204, v212, vcc
	s_add_u32 s6, s88, s6
	v_writelane_b32 v254, s8, 21
	v_lshlrev_b32_e32 v70, 2, v32
	s_addc_u32 s7, s89, s7
	v_writelane_b32 v254, s9, 22
	s_mov_b32 s8, s10
	s_movk_i32 s10, 0x1000
	s_mov_b32 s11, 0x800000
	v_lshl_add_u64 v[72:73], s[0:1], 0, v[160:161]
	v_add_co_u32_e32 v72, vcc, 0x15f20000, v72
	s_add_u32 s0, s0, s4
	s_addc_u32 s1, s1, s5
	v_addc_co_u32_e32 v73, vcc, 0, v73, vcc
	v_add_co_u32_e32 v74, vcc, 0x1000, v72
	global_load_dwordx4 v[96:99], v[72:73], off
	global_load_dwordx4 v[100:103], v[72:73], off offset:1024
	v_addc_co_u32_e32 v75, vcc, 0, v73, vcc
	global_load_dwordx4 v[104:107], v[72:73], off offset:2048
	global_load_dwordx4 v[108:111], v[72:73], off offset:3072
	global_load_dwordx4 v[112:115], v[74:75], off
	global_load_dwordx4 v[116:119], v[74:75], off offset:1024
	global_load_dwordx4 v[120:123], v[74:75], off offset:2048
	global_load_dwordx4 v[124:127], v[74:75], off offset:3072
	s_waitcnt vmcnt(0)
	s_branch .Lfin_have
.Lfin_loop:
	s_waitcnt vmcnt(8)
; DEV float wsum(float v) { for (int o = 32; o > 0; o >>= 1) v += __shfl_xor(v, o); return v; }
; DEV u32x2 pack4(f32x4 a) { u32x2 w; w.x = cvt_pk_bf16(a[0], a[1]); w.y = cvt_pk_bf16(a[2], a[3]); return w; }
; template <bool OUTF>
; DEV void rmsnorm_rows(const float* __restrict__ x, const float* __restrict__ g, void* outp, int rows, int gwave, int nwaves, int lane) {
;     for (int r = gwave; r < rows; r += nwaves) {
;         const f32x4* xr = (const f32x4*)(x + (size_t)r * 2048); f32x4 v[8]; float ss = 0.f;
; #pragma unroll
;         for (int i = 0; i < 8; ++i) { v[i] = xr[lane + 64 * i]; ss += v[i][0] * v[i][0] + v[i][1] * v[i][1] + v[i][2] * v[i][2] + v[i][3] * v[i][3]; }
;         ss = wsum(ss); const float rs = rsqrtf(ss * (1.0f / 2048.0f) + EPS);
; #pragma unroll
;         for (int i = 0; i < 8; ++i) { const f32x4 gg = ((const f32x4*)g)[lane + 64 * i]; const f32x4 o = (v[i] * rs) * gg;
;             if (OUTF) ((f32x4*)((float*)outp + (size_t)r * 2048))[lane + 64 * i] = o;
;             else ((u32x2*)((u16*)outp + (size_t)r * 2048))[lane + 64 * i] = pack4(o); }
;     }
.Lfin_have:
	v_mov_b64_e32 v[32:33], v[96:97]
	v_mov_b64_e32 v[34:35], v[98:99]
	v_mov_b64_e32 v[36:37], v[100:101]
	v_mov_b64_e32 v[38:39], v[102:103]
	v_mov_b64_e32 v[40:41], v[104:105]
	v_mov_b64_e32 v[42:43], v[106:107]
	v_mov_b64_e32 v[44:45], v[108:109]
	v_mov_b64_e32 v[46:47], v[110:111]
	v_mov_b64_e32 v[48:49], v[112:113]
	v_mov_b64_e32 v[50:51], v[114:115]
	v_mov_b64_e32 v[52:53], v[116:117]
	v_mov_b64_e32 v[54:55], v[118:119]
	v_mov_b64_e32 v[56:57], v[120:121]
	v_mov_b64_e32 v[58:59], v[122:123]
	v_mov_b64_e32 v[60:61], v[124:125]
	v_mov_b64_e32 v[62:63], v[126:127]
	s_add_i32 s8, s8, s12
	s_cmpk_gt_i32 s8, 0x1fff
	s_cselect_b32 s9, 0, 1
	s_cbranch_scc1 .Lfin_proc
	v_lshl_add_u64 v[72:73], s[0:1], 0, v[160:161]
	v_add_co_u32_e32 v72, vcc, 0x15f20000, v72
	s_add_u32 s0, s0, s4
	s_addc_u32 s1, s1, s5
	v_addc_co_u32_e32 v73, vcc, 0, v73, vcc
	v_add_co_u32_e32 v74, vcc, 0x1000, v72
	global_load_dwordx4 v[96:99], v[72:73], off
	global_load_dwordx4 v[100:103], v[72:73], off offset:1024
	v_addc_co_u32_e32 v75, vcc, 0, v73, vcc
	global_load_dwordx4 v[104:107], v[72:73], off offset:2048
	global_load_dwordx4 v[108:111], v[72:73], off offset:3072
	global_load_dwordx4 v[112:115], v[74:75], off
	global_load_dwordx4 v[116:119], v[74:75], off offset:1024
	global_load_dwordx4 v[120:123], v[74:75], off offset:2048
	global_load_dwordx4 v[124:127], v[74:75], off offset:3072
.Lfin_proc:
	v_mul_f32_e32 v76, v33, v33
	v_mul_f32_e32 v77, v37, v37
	v_mul_f32_e32 v78, v41, v41
	v_mul_f32_e32 v79, v45, v45
	v_mul_f32_e32 v80, v49, v49
	v_mul_f32_e32 v81, v53, v53
	v_mul_f32_e32 v82, v57, v57
	v_mul_f32_e32 v83, v61, v61
	v_fmac_f32_e32 v76, v32, v32
	v_fmac_f32_e32 v77, v36, v36
	v_fmac_f32_e32 v78, v40, v40
	v_fmac_f32_e32 v79, v44, v44
	v_fmac_f32_e32 v80, v48, v48
	v_fmac_f32_e32 v81, v52, v52
	v_fmac_f32_e32 v82, v56, v56
	v_fmac_f32_e32 v83, v60, v60
	v_fmac_f32_e32 v76, v34, v34
	v_fmac_f32_e32 v77, v38, v38
	v_fmac_f32_e32 v78, v42, v42
	v_fmac_f32_e32 v79, v46, v46
	v_fmac_f32_e32 v80, v50, v50
	v_fmac_f32_e32 v81, v54, v54
	v_fmac_f32_e32 v82, v58, v58
	v_fmac_f32_e32 v83, v62, v62
	v_fmac_f32_e32 v76, v35, v35
	v_fmac_f32_e32 v77, v39, v39
	v_fmac_f32_e32 v78, v43, v43
	v_fmac_f32_e32 v79, v47, v47
	v_fmac_f32_e32 v80, v51, v51
	v_fmac_f32_e32 v81, v55, v55
	v_fmac_f32_e32 v82, v59, v59
	v_fmac_f32_e32 v83, v63, v63
	v_add_f32_e32 v76, v76, v77
	v_add_f32_e32 v78, v78, v79
	v_add_f32_e32 v80, v80, v81
	v_add_f32_e32 v82, v82, v83
	v_add_f32_e32 v76, v76, v78
	v_add_f32_e32 v80, v80, v82
	v_add_f32_e32 v76, v76, v80
	ds_bpermute_b32 v77, v65, v76
	s_waitcnt lgkmcnt(0)
	v_add_f32_e32 v76, v76, v77
	ds_bpermute_b32 v77, v66, v76
	s_waitcnt lgkmcnt(0)
	v_add_f32_e32 v76, v76, v77
	ds_bpermute_b32 v77, v67, v76
	s_waitcnt lgkmcnt(0)
	v_add_f32_e32 v76, v76, v77
	ds_bpermute_b32 v77, v68, v76
	s_waitcnt lgkmcnt(0)
	v_add_f32_e32 v76, v76, v77
	ds_bpermute_b32 v77, v69, v76
	s_waitcnt lgkmcnt(0)
	v_add_f32_e32 v76, v76, v77
	ds_bpermute_b32 v77, v70, v76
	s_waitcnt lgkmcnt(0)
	v_add_f32_e32 v76, v76, v77
	v_fmamk_f32 v76, v76, 0x3a000000, v199
	v_rsq_f32_e32 v76, v76
	v_lshl_add_u64 v[84:85], s[6:7], 0, v[160:161]
	v_add_co_u32_e32 v86, vcc, 0x1000, v84
	s_nop 1
	v_addc_co_u32_e32 v87, vcc, 0, v85, vcc
	v_pk_mul_f32 v[32:33], v[32:33], v[76:77] op_sel_hi:[1,0]
	v_pk_mul_f32 v[34:35], v[34:35], v[76:77] op_sel_hi:[1,0]
	v_pk_mul_f32 v[32:33], v[0:1], v[32:33]
	v_pk_mul_f32 v[34:35], v[2:3], v[34:35]
	global_store_dwordx4 v[84:85], v[32:35], off
	v_pk_mul_f32 v[36:37], v[36:37], v[76:77] op_sel_hi:[1,0]
	v_pk_mul_f32 v[38:39], v[38:39], v[76:77] op_sel_hi:[1,0]
	v_pk_mul_f32 v[36:37], v[4:5], v[36:37]
	v_pk_mul_f32 v[38:39], v[6:7], v[38:39]
	global_store_dwordx4 v[84:85], v[36:39], off offset:1024
	v_pk_mul_f32 v[40:41], v[40:41], v[76:77] op_sel_hi:[1,0]
	v_pk_mul_f32 v[42:43], v[42:43], v[76:77] op_sel_hi:[1,0]
	v_pk_mul_f32 v[40:41], v[8:9], v[40:41]
	v_pk_mul_f32 v[42:43], v[10:11], v[42:43]
	global_store_dwordx4 v[84:85], v[40:43], off offset:2048
	v_pk_mul_f32 v[44:45], v[44:45], v[76:77] op_sel_hi:[1,0]
	v_pk_mul_f32 v[46:47], v[46:47], v[76:77] op_sel_hi:[1,0]
	v_pk_mul_f32 v[44:45], v[12:13], v[44:45]
	v_pk_mul_f32 v[46:47], v[14:15], v[46:47]
	global_store_dwordx4 v[84:85], v[44:47], off offset:3072
	v_pk_mul_f32 v[48:49], v[48:49], v[76:77] op_sel_hi:[1,0]
	v_pk_mul_f32 v[50:51], v[50:51], v[76:77] op_sel_hi:[1,0]
	v_pk_mul_f32 v[48:49], v[16:17], v[48:49]
	v_pk_mul_f32 v[50:51], v[18:19], v[50:51]
	global_store_dwordx4 v[86:87], v[48:51], off
	v_pk_mul_f32 v[52:53], v[52:53], v[76:77] op_sel_hi:[1,0]
	v_pk_mul_f32 v[54:55], v[54:55], v[76:77] op_sel_hi:[1,0]
	v_pk_mul_f32 v[52:53], v[20:21], v[52:53]
	v_pk_mul_f32 v[54:55], v[22:23], v[54:55]
	global_store_dwordx4 v[86:87], v[52:55], off offset:1024
	v_pk_mul_f32 v[56:57], v[56:57], v[76:77] op_sel_hi:[1,0]
	v_pk_mul_f32 v[58:59], v[58:59], v[76:77] op_sel_hi:[1,0]
	v_pk_mul_f32 v[56:57], v[24:25], v[56:57]
	v_pk_mul_f32 v[58:59], v[26:27], v[58:59]
	global_store_dwordx4 v[86:87], v[56:59], off offset:2048
	v_pk_mul_f32 v[60:61], v[60:61], v[76:77] op_sel_hi:[1,0]
	v_pk_mul_f32 v[62:63], v[62:63], v[76:77] op_sel_hi:[1,0]
	v_pk_mul_f32 v[60:61], v[28:29], v[60:61]
	v_pk_mul_f32 v[62:63], v[30:31], v[62:63]
	global_store_dwordx4 v[86:87], v[60:63], off offset:3072
	s_add_u32 s6, s6, s4
	s_addc_u32 s7, s7, s5
	s_cmp_lg_u32 s9, 0
	s_cbranch_scc1 .Lfin_loop
	v_writelane_b32 v254, s12, 24
	s_nop 1
	v_writelane_b32 v254, s13, 25
